# nt (non-temporal) hint on the sample-group state stream loads/stores in recur1 (read-once inputs, write-once final outputs), on v13
# speedup vs baseline: 1.0067x; 1.0067x over previous
; #define LAUNDER_PTR(p) do {} while (0)
; #define LAUNDER_PTR(p) asm volatile("" : "+v"(p))
; __device__ __forceinline__ void hgrn_sample_load(f32x4 (&st)[8], const float* state_in, int bh, int tid) {
;     const float* sp = state_in + (size_t)bh * 16384 + tid * 4;
; #pragma unroll
;     for (int it = 0; it < 8; ++it) { LAUNDER_PTR(sp); st[it] = *(const f32x4*)sp; sp += 2048; }
; }
.LBB0_403:
	v_readlane_b32 s2, v255, 34
	v_readlane_b32 s4, v253, 15
	v_readlane_b32 s3, v255, 35
	v_readlane_b32 s5, v253, 16
	s_lshl_b64 s[2:3], s[2:3], 26
	v_readlane_b32 s8, v253, 19
	v_readlane_b32 s16, v253, 27
	v_readlane_b32 s4, v254, 11
	v_readlane_b32 s9, v253, 20
	v_readlane_b32 s17, v253, 28
	s_add_u32 s16, s8, s2
	v_readlane_b32 s5, v254, 12
	s_addc_u32 s17, s9, s3
	s_and_b64 vcc, exec, s[4:5]
	v_readlane_b32 s6, v253, 17
	v_readlane_b32 s7, v253, 18
	v_readlane_b32 s10, v253, 21
	v_readlane_b32 s11, v253, 22
	v_readlane_b32 s12, v253, 23
	v_readlane_b32 s13, v253, 24
	v_readlane_b32 s14, v253, 25
	v_readlane_b32 s15, v253, 26
	v_readlane_b32 s18, v253, 29
	v_readlane_b32 s19, v253, 30
	s_cbranch_vccz .LBB0_405
	v_mov_b32_e32 v0, v138
	v_readlane_b32 s4, v255, 4
	v_readlane_b32 s5, v255, 5
	s_add_u32 s4, s16, s4
	v_lshlrev_b32_e32 v0, 2, v0
	s_addc_u32 s5, s17, s5
	v_ashrrev_i32_e32 v1, 31, v0
	v_lshl_add_u64 v[4:5], v[0:1], 2, s[4:5]
	global_load_dwordx4 v[0:3], v[4:5], off nt
	v_lshl_add_u64 v[8:9], v[4:5], 0, s[44:45]
	global_load_dwordx4 v[4:7], v[8:9], off nt
	v_lshl_add_u64 v[8:9], v[8:9], 0, s[44:45]
	global_load_dwordx4 v[12:15], v[8:9], off nt
	v_lshl_add_u64 v[8:9], v[8:9], 0, s[44:45]
	global_load_dwordx4 v[16:19], v[8:9], off nt
	v_lshl_add_u64 v[8:9], v[8:9], 0, s[44:45]
	global_load_dwordx4 v[20:23], v[8:9], off nt
	v_lshl_add_u64 v[8:9], v[8:9], 0, s[44:45]
	global_load_dwordx4 v[24:27], v[8:9], off nt
	v_lshl_add_u64 v[8:9], v[8:9], 0, s[44:45]
	global_load_dwordx4 v[28:31], v[8:9], off nt
	v_lshl_add_u64 v[8:9], v[8:9], 0, s[44:45]
	global_load_dwordx4 v[32:35], v[8:9], off nt

; #define LAS __attribute__((address_space(3)))
; #define LAUNDER_PTR(p) do {} while (0)
; #define LAUNDER_PTR(p) asm volatile("" : "+v"(p))
; __device__ __forceinline__ void hgrn_sample_step(const bf16* proj, const float* lbs_l, const float* hgn_l, const float* state_in, float* state_out, bf16* ohg, int bh, int tid, LAS unsigned char* lds,
;                                                  f32x4 (&st)[8], int bh_next) {
;     ...
;     const int dv4 = tid & 31, rg = tid >> 5;
;     const f32x4 vv = *(const LAS f32x4*)(sv + 4 * dv4);
;     f32x4 oacc = (f32x4){0.f, 0.f, 0.f, 0.f};
;     float* op = state_out + (size_t)bh * 16384 + tid * 4;
;     const float* np = state_in + (size_t)(bh_next >= 0 ? bh_next : bh) * 16384 + tid * 4;
; #pragma unroll
;     for (int it = 0; it < 8; ++it) { const int dk = it * 16 + rg; const f32x4 sn = st[it] * sg[dk] + vv * sk[dk]; LAUNDER_PTR(op); *(f32x4*)op = sn; op += 2048; oacc = oacc + sn * sq[dk];
;         LAUNDER_PTR(np); if (bh_next >= 0) st[it] = *(const f32x4*)np; np += 2048; }
;     *(LAS f32x4*)(so + rg * 128 + 4 * dv4) = oacc;
.LBB0_412:
	s_or_b64 exec, exec, s[8:9]
	v_lshlrev_b32_e32 v40, 2, v8
	v_and_b32_e32 v73, 0x7c, v40
	v_ashrrev_i32_e32 v71, 5, v8
	v_lshl_add_u32 v10, v73, 2, 0
	s_waitcnt lgkmcnt(0)
	s_barrier
	ds_read_b128 v[36:39], v10 offset:1536
	v_lshl_add_u32 v10, v71, 2, 0
	ds_read2st64_b32 v[42:43], v10 offset0:2 offset1:4
	s_add_i32 s19, s22, s90
	s_cmpk_gt_i32 s19, 0x3ff
	s_cselect_b64 s[12:13], -1, 0
	s_cmpk_lt_i32 s19, 0x400
	s_cselect_b32 s8, s19, -1
	v_ashrrev_i32_e32 v41, 31, v40
	v_lshlrev_b64 v[46:47], 2, v[40:41]
	s_cmp_gt_i32 s8, -1
	s_waitcnt lgkmcnt(0)
	v_mov_b32_e32 v40, v43
	s_cselect_b64 s[14:15], -1, 0
	v_pk_mul_f32 v[48:49], v[38:39], v[40:41] op_sel_hi:[1,0]
	v_pk_mul_f32 v[40:41], v[36:37], v[40:41] op_sel_hi:[1,0]
	v_lshl_add_u64 v[44:45], s[2:3], 0, v[46:47]
	s_and_b64 vcc, s[14:15], exec
	s_waitcnt vmcnt(0)
	v_pk_fma_f32 v[40:41], v[0:1], v[42:43], v[40:41] op_sel_hi:[1,0,1]
	v_pk_fma_f32 v[42:43], v[2:3], v[42:43], v[48:49] op_sel_hi:[1,0,1]
	s_cselect_b32 s8, s8, s22
	global_store_dwordx4 v[44:45], v[40:43], off nt
	s_ashr_i32 s9, s8, 31
	ds_read_b32 v70, v10
	s_lshl_b64 s[8:9], s[8:9], 16
	s_add_u32 s8, s16, s8
	s_addc_u32 s9, s17, s9
	v_lshl_add_u64 v[46:47], s[8:9], 0, v[46:47]
	s_cbranch_vccz .LBB0_414
	global_load_dwordx4 v[0:3], v[46:47], off nt
.LBB0_414:
	v_add_u32_e32 v66, 64, v10
	ds_read2st64_b32 v[50:51], v66 offset0:2 offset1:4
	v_lshl_add_u64 v[48:49], v[44:45], 0, s[44:45]
	v_lshl_add_u64 v[52:53], v[46:47], 0, s[44:45]
	s_andn2_b64 vcc, exec, s[14:15]
	s_waitcnt lgkmcnt(0)
	v_mov_b32_e32 v44, v51
	v_pk_mul_f32 v[46:47], v[38:39], v[44:45] op_sel_hi:[1,0]
	v_pk_mul_f32 v[44:45], v[36:37], v[44:45] op_sel_hi:[1,0]
	v_pk_fma_f32 v[46:47], v[6:7], v[50:51], v[46:47] op_sel_hi:[1,0,1]
	v_pk_fma_f32 v[44:45], v[4:5], v[50:51], v[44:45] op_sel_hi:[1,0,1]
	global_store_dwordx4 v[48:49], v[44:47], off nt
	ds_read_b32 v72, v10 offset:64
	v_cndmask_b32_e64 v50, 0, 1, s[14:15]
	v_cmp_ne_u32_e64 s[8:9], 1, v50
	s_cbranch_vccnz .LBB0_416
	global_load_dwordx4 v[4:7], v[52:53], off nt
.LBB0_416:
	v_add_u32_e32 v75, 0x80, v10
	ds_read2st64_b32 v[56:57], v75 offset0:2 offset1:4
	v_lshl_add_u64 v[54:55], v[48:49], 0, s[44:45]
	s_and_b64 vcc, exec, s[8:9]
	s_waitcnt lgkmcnt(0)
	v_mov_b32_e32 v48, v57
	v_pk_mul_f32 v[50:51], v[38:39], v[48:49] op_sel_hi:[1,0]
	v_pk_mul_f32 v[48:49], v[36:37], v[48:49] op_sel_hi:[1,0]
	v_pk_fma_f32 v[50:51], v[14:15], v[56:57], v[50:51] op_sel_hi:[1,0,1]
	v_pk_fma_f32 v[48:49], v[12:13], v[56:57], v[48:49] op_sel_hi:[1,0,1]
	global_store_dwordx4 v[54:55], v[48:51], off nt
	ds_read_b32 v74, v10 offset:128
	v_lshl_add_u64 v[56:57], v[52:53], 0, s[44:45]
	s_cbranch_vccnz .LBB0_418
	global_load_dwordx4 v[12:15], v[56:57], off nt
.LBB0_418:
	v_add_u32_e32 v77, 0xc0, v10
	ds_read2st64_b32 v[52:53], v77 offset0:2 offset1:4
	v_lshl_add_u64 v[58:59], v[54:55], 0, s[44:45]
	s_and_b64 vcc, exec, s[8:9]
	s_waitcnt lgkmcnt(0)
	v_mov_b32_e32 v54, v53
	v_pk_mul_f32 v[60:61], v[38:39], v[54:55] op_sel_hi:[1,0]
	v_pk_mul_f32 v[62:63], v[36:37], v[54:55] op_sel_hi:[1,0]
	v_pk_fma_f32 v[54:55], v[18:19], v[52:53], v[60:61] op_sel_hi:[1,0,1]
	v_pk_fma_f32 v[52:53], v[16:17], v[52:53], v[62:63] op_sel_hi:[1,0,1]
	global_store_dwordx4 v[58:59], v[52:55], off nt
	ds_read_b32 v76, v10 offset:192
	v_lshl_add_u64 v[60:61], v[56:57], 0, s[44:45]
	s_cbranch_vccnz .LBB0_420
	global_load_dwordx4 v[16:19], v[60:61], off nt
.LBB0_420:
	ds_read2st64_b32 v[56:57], v10 offset0:3 offset1:5
	v_lshl_add_u64 v[62:63], v[58:59], 0, s[44:45]
	s_and_b64 vcc, exec, s[8:9]
	s_waitcnt lgkmcnt(0)
	v_mov_b32_e32 v58, v57
	v_pk_mul_f32 v[64:65], v[38:39], v[58:59] op_sel_hi:[1,0]
	v_pk_mul_f32 v[78:79], v[36:37], v[58:59] op_sel_hi:[1,0]
	v_pk_fma_f32 v[58:59], v[22:23], v[56:57], v[64:65] op_sel_hi:[1,0,1]
	v_pk_fma_f32 v[56:57], v[20:21], v[56:57], v[78:79] op_sel_hi:[1,0,1]
	global_store_dwordx4 v[62:63], v[56:59], off nt
	ds_read_b32 v78, v10 offset:256
	v_lshl_add_u64 v[64:65], v[60:61], 0, s[44:45]
	s_cbranch_vccnz .LBB0_422
	global_load_dwordx4 v[20:23], v[64:65], off nt
.LBB0_422:
	ds_read2st64_b32 v[60:61], v66 offset0:3 offset1:5
	v_lshl_add_u64 v[66:67], v[62:63], 0, s[44:45]
	v_lshl_add_u64 v[84:85], v[64:65], 0, s[44:45]
	s_and_b64 vcc, exec, s[8:9]
	s_waitcnt lgkmcnt(0)
	v_mov_b32_e32 v62, v61
	v_pk_mul_f32 v[80:81], v[38:39], v[62:63] op_sel_hi:[1,0]
	v_pk_mul_f32 v[82:83], v[36:37], v[62:63] op_sel_hi:[1,0]
	v_pk_fma_f32 v[62:63], v[26:27], v[60:61], v[80:81] op_sel_hi:[1,0,1]
	v_pk_fma_f32 v[60:61], v[24:25], v[60:61], v[82:83] op_sel_hi:[1,0,1]
	global_store_dwordx4 v[66:67], v[60:63], off nt
	ds_read_b32 v80, v10 offset:320
	s_cbranch_vccnz .LBB0_424
	global_load_dwordx4 v[24:27], v[84:85], off nt
.LBB0_424:
	ds_read2st64_b32 v[64:65], v75 offset0:3 offset1:5
	v_lshl_add_u64 v[86:87], v[66:67], 0, s[44:45]
	s_and_b64 vcc, exec, s[8:9]
	s_waitcnt lgkmcnt(0)
	v_mov_b32_e32 v66, v65
	v_pk_mul_f32 v[82:83], v[38:39], v[66:67] op_sel_hi:[1,0]
	v_pk_mul_f32 v[88:89], v[36:37], v[66:67] op_sel_hi:[1,0]
	v_pk_fma_f32 v[66:67], v[30:31], v[64:65], v[82:83] op_sel_hi:[1,0,1]
	v_pk_fma_f32 v[64:65], v[28:29], v[64:65], v[88:89] op_sel_hi:[1,0,1]
	global_store_dwordx4 v[86:87], v[64:67], off nt
	ds_read_b32 v82, v10 offset:384
	v_lshl_add_u64 v[88:89], v[84:85], 0, s[44:45]
	s_cbranch_vccnz .LBB0_426
	global_load_dwordx4 v[28:31], v[88:89], off nt
.LBB0_426:
	ds_read2st64_b32 v[84:85], v77 offset0:3 offset1:5
	v_lshl_add_u64 v[86:87], v[86:87], 0, s[44:45]
	s_and_b64 vcc, exec, s[8:9]
	s_waitcnt lgkmcnt(0)
	v_mov_b32_e32 v90, v85
	v_pk_mul_f32 v[38:39], v[38:39], v[90:91] op_sel_hi:[1,0]
	v_pk_mul_f32 v[36:37], v[36:37], v[90:91] op_sel_hi:[1,0]
	v_pk_fma_f32 v[38:39], v[34:35], v[84:85], v[38:39] op_sel_hi:[1,0,1]
	v_pk_fma_f32 v[36:37], v[32:33], v[84:85], v[36:37] op_sel_hi:[1,0,1]
	global_store_dwordx4 v[86:87], v[36:39], off nt
	ds_read_b32 v84, v10 offset:448
	v_lshl_add_u64 v[86:87], v[88:89], 0, s[44:45]
	s_cbranch_vccnz .LBB0_428
	global_load_dwordx4 v[32:35], v[86:87], off nt

; #define LAUNDER_PTR(p) do {} while (0)
; #define LAUNDER_PTR(p) asm volatile("" : "+v"(p))
; __device__ __forceinline__ void ssd_sample_load(f32x4 (&st)[16], const float* state_in, int bg, int tid) {
;     const float* sp = state_in + ((size_t)((bg >> 3) * 32 + (bg & 7) * 4)) * 8192 + tid * 4;
; #pragma unroll
;     for (int it = 0; it < 16; ++it) { LAUNDER_PTR(sp); st[it] = *(const f32x4*)sp; sp += 2048; }
; }
.LBB0_434:
	v_readlane_b32 s2, v255, 34
	v_readlane_b32 s3, v255, 35
	v_readlane_b32 s8, v253, 15
	s_lshl_b64 s[2:3], s[2:3], 27
	v_readlane_b32 s14, v253, 21
	v_readlane_b32 s20, v253, 27
	v_readlane_b32 s15, v253, 22
	v_readlane_b32 s21, v253, 28
	s_add_u32 s20, s14, s2
	s_addc_u32 s21, s15, s3
	v_readlane_b32 s2, v254, 11
	v_readlane_b32 s3, v254, 12
	s_and_b64 vcc, exec, s[2:3]
	v_readlane_b32 s9, v253, 16
	v_readlane_b32 s10, v253, 17
	v_readlane_b32 s11, v253, 18
	v_readlane_b32 s12, v253, 19
	v_readlane_b32 s13, v253, 20
	v_readlane_b32 s16, v253, 23
	v_readlane_b32 s17, v253, 24
	v_readlane_b32 s18, v253, 25
	v_readlane_b32 s19, v253, 26
	v_readlane_b32 s22, v253, 29
	v_readlane_b32 s23, v253, 30
	s_cbranch_vccz .LBB0_436
	s_waitcnt vmcnt(0) lgkmcnt(0)
	v_mov_b32_e32 v0, v138
	v_readlane_b32 s2, v254, 15
	v_readlane_b32 s3, v254, 16
	s_add_u32 s2, s20, s2
	v_lshlrev_b32_e32 v0, 2, v0
	s_addc_u32 s3, s21, s3
	v_ashrrev_i32_e32 v1, 31, v0
	v_lshl_add_u64 v[4:5], v[0:1], 2, s[2:3]
	global_load_dwordx4 v[0:3], v[4:5], off nt
	v_lshl_add_u64 v[8:9], v[4:5], 0, s[44:45]
	global_load_dwordx4 v[4:7], v[8:9], off nt
	v_lshl_add_u64 v[8:9], v[8:9], 0, s[44:45]
	global_load_dwordx4 v[12:15], v[8:9], off nt
	v_lshl_add_u64 v[8:9], v[8:9], 0, s[44:45]
	global_load_dwordx4 v[16:19], v[8:9], off nt
	v_lshl_add_u64 v[8:9], v[8:9], 0, s[44:45]
	global_load_dwordx4 v[20:23], v[8:9], off nt
	v_lshl_add_u64 v[8:9], v[8:9], 0, s[44:45]
	global_load_dwordx4 v[24:27], v[8:9], off nt
	v_lshl_add_u64 v[8:9], v[8:9], 0, s[44:45]
	global_load_dwordx4 v[28:31], v[8:9], off nt
	v_lshl_add_u64 v[8:9], v[8:9], 0, s[44:45]
	global_load_dwordx4 v[32:35], v[8:9], off nt
	v_lshl_add_u64 v[8:9], v[8:9], 0, s[44:45]
	global_load_dwordx4 v[36:39], v[8:9], off nt
	v_lshl_add_u64 v[8:9], v[8:9], 0, s[44:45]
	global_load_dwordx4 v[40:43], v[8:9], off nt
	v_lshl_add_u64 v[8:9], v[8:9], 0, s[44:45]
	global_load_dwordx4 v[44:47], v[8:9], off nt
	v_lshl_add_u64 v[8:9], v[8:9], 0, s[44:45]
	global_load_dwordx4 v[48:51], v[8:9], off nt
	v_lshl_add_u64 v[8:9], v[8:9], 0, s[44:45]
	global_load_dwordx4 v[52:55], v[8:9], off nt
	v_lshl_add_u64 v[8:9], v[8:9], 0, s[44:45]
	global_load_dwordx4 v[56:59], v[8:9], off nt
	v_lshl_add_u64 v[8:9], v[8:9], 0, s[44:45]
	global_load_dwordx4 v[60:63], v[8:9], off nt
	v_lshl_add_u64 v[8:9], v[8:9], 0, s[44:45]
	global_load_dwordx4 v[64:67], v[8:9], off nt

; #define LAS __attribute__((address_space(3)))
; #define LAUNDER_PTR(p) do {} while (0)
; #define LAUNDER_PTR(p) asm volatile("" : "+v"(p))
; __device__ __forceinline__ float row32_sum(float s) { s += SHFL_XOR(s, 1); s += SHFL_XOR(s, 2); s += SHFL_XOR(s, 4); s += SHFL_XOR(s, 8); s += SHFL_XOR(s, 16); return s; }
; __device__ __forceinline__ void ssd_sample_step(const bf16* proj, const float* conv_w, const float* conv_b, const float* dt_bias, const float* a_log, const float* d_skip, const float* ssm_norm, ...
;     ...
;     const int n4 = tid & 31, pr_ = tid >> 5;
;     const f32x4 Bv = *(const LAS f32x4*)(sB + 4 * n4), Cv = *(const LAS f32x4*)(sC + 4 * n4);
;     float* op = state_out + ((size_t)(b * 32 + grp * 4)) * 8192 + tid * 4;
;     const int bgn = bg_next >= 0 ? bg_next : bg; const float* np = state_in + ((size_t)((bgn >> 3) * 32 + (bgn & 7) * 4)) * 8192 + tid * 4;
; #pragma unroll
;     for (int it = 0; it < 16; ++it) { const int k = it >> 2, p = (it & 3) * 16 + pr_; const float xdt = sx[k * 64 + p] * sdt[k];
;         const f32x4 hn = st[it] * sdec[k] + Bv * xdt; LAUNDER_PTR(op); *(f32x4*)op = hn; op += 2048;
;         LAUNDER_PTR(np); if (bg_next >= 0) st[it] = *(const f32x4*)np; np += 2048;
;         const f32x4 t = hn * Cv; float y = (t[0] + t[1]) + (t[2] + t[3]); y = row32_sum(y);
;         if ((lane & 31) == 0) sy[k * 64 + p] = y; }
.LBB0_461:
	s_or_b64 exec, exec, s[6:7]
	s_add_i32 s51, s59, s90
	s_cmpk_gt_i32 s51, 0x3ff
	s_cselect_b64 s[12:13], -1, 0
	s_cmpk_lt_i32 s51, 0x400
	s_cselect_b32 s8, s51, -1
	s_lshl_b32 s6, s58, 5
	s_lshl_b32 s58, s50, 2
	s_or_b32 s6, s6, s58
	s_ashr_i32 s7, s6, 31
	s_lshl_b64 s[6:7], s[6:7], 15
	s_add_u32 s6, s64, s6
	v_lshlrev_b32_e32 v72, 2, v8
	s_addc_u32 s7, s66, s7
	v_ashrrev_i32_e32 v73, 31, v72
	s_cmp_gt_i32 s8, -1
	v_lshlrev_b32_e32 v68, 4, v8
	v_lshlrev_b64 v[76:77], 2, v[72:73]
	s_cselect_b64 s[14:15], -1, 0
	v_ashrrev_i32_e32 v9, 5, v8
	v_and_b32_e32 v68, 0x1f0, v68
	v_lshl_add_u64 v[82:83], s[6:7], 0, v[76:77]
	s_and_b64 s[6:7], s[14:15], exec
	s_movk_i32 s9, 0x1000
	v_add_u32_e32 v74, 0, v68
	s_cselect_b32 s6, s8, s59
	v_lshl_add_u32 v81, v9, 2, 0
	v_add_u32_e64 v9, s9, 0
	s_waitcnt lgkmcnt(0)
	s_barrier
	ds_read_b128 v[68:71], v74 offset:3584
	s_lshl_b32 s6, s6, 2
	ds_read_b128 v[72:75], v74 offset:3072
	ds_read_b32 v86, v81 offset:2048
	ds_read2_b32 v[78:79], v9 offset1:4
	s_ashr_i32 s7, s6, 31
	s_lshl_b64 s[6:7], s[6:7], 15
	s_add_u32 s6, s20, s6
	s_addc_u32 s7, s21, s7
	v_lshl_add_u64 v[84:85], s[6:7], 0, v[76:77]
	s_waitcnt lgkmcnt(0)
	v_mov_b32_e32 v76, v79
	v_mul_f32_e32 v78, v86, v78
	v_pk_mul_f32 v[86:87], v[2:3], v[76:77] op_sel_hi:[1,0]
	v_pk_mul_f32 v[76:77], v[0:1], v[76:77] op_sel_hi:[1,0]
	s_cmp_lt_i32 s8, 0
	v_pk_fma_f32 v[76:77], v[72:73], v[78:79], v[76:77] op_sel_hi:[1,0,1]
	v_pk_fma_f32 v[78:79], v[74:75], v[78:79], v[86:87] op_sel_hi:[1,0,1]
	global_store_dwordx4 v[82:83], v[76:79], off nt
	s_cbranch_scc1 .LBB0_463
	global_load_dwordx4 v[0:3], v[84:85], off nt

; #define LAUNDER_PTR(p) do {} while (0)
; #define LAUNDER_PTR(p) asm volatile("" : "+v"(p))
; __device__ __forceinline__ float row32_sum(float s) { s += SHFL_XOR(s, 1); s += SHFL_XOR(s, 2); s += SHFL_XOR(s, 4); s += SHFL_XOR(s, 8); s += SHFL_XOR(s, 16); return s; }
; __device__ __forceinline__ void ssd_sample_step(const bf16* proj, const float* conv_w, const float* conv_b, const float* dt_bias, const float* a_log, const float* d_skip, const float* ssm_norm, ...
;     ...
; #pragma unroll
;     for (int it = 0; it < 16; ++it) { const int k = it >> 2, p = (it & 3) * 16 + pr_; const float xdt = sx[k * 64 + p] * sdt[k];
;         const f32x4 hn = st[it] * sdec[k] + Bv * xdt; LAUNDER_PTR(op); *(f32x4*)op = hn; op += 2048;
;         LAUNDER_PTR(np); if (bg_next >= 0) st[it] = *(const f32x4*)np; np += 2048;
;         const f32x4 t = hn * Cv; float y = (t[0] + t[1]) + (t[2] + t[3]); y = row32_sum(y);
;         if ((lane & 31) == 0) sy[k * 64 + p] = y; }
.LBB0_465:
	s_or_b64 exec, exec, s[8:9]
	ds_read_b32 v78, v81 offset:2112
	s_waitcnt lgkmcnt(0)
	ds_read2_b32 v[76:77], v9 offset1:4
	v_lshl_add_u64 v[84:85], v[84:85], 0, s[44:45]
	v_lshl_add_u64 v[82:83], v[82:83], 0, s[44:45]
	s_andn2_b64 vcc, exec, s[14:15]
	s_waitcnt lgkmcnt(0)
	v_mul_f32_e32 v76, v78, v76
	v_mov_b32_e32 v78, v77
	v_pk_mul_f32 v[86:87], v[6:7], v[78:79] op_sel_hi:[1,0]
	v_pk_mul_f32 v[88:89], v[4:5], v[78:79] op_sel_hi:[1,0]
	v_pk_fma_f32 v[78:79], v[74:75], v[76:77], v[86:87] op_sel_hi:[1,0,1]
	v_cndmask_b32_e64 v86, 0, 1, s[14:15]
	v_pk_fma_f32 v[76:77], v[72:73], v[76:77], v[88:89] op_sel_hi:[1,0,1]
	v_cmp_ne_u32_e64 s[8:9], 1, v86
	global_store_dwordx4 v[82:83], v[76:79], off nt
	s_cbranch_vccnz .LBB0_467
	global_load_dwordx4 v[4:7], v[84:85], off nt

; #define LAUNDER_PTR(p) do {} while (0)
; #define LAUNDER_PTR(p) asm volatile("" : "+v"(p))
; __device__ __forceinline__ float row32_sum(float s) { s += SHFL_XOR(s, 1); s += SHFL_XOR(s, 2); s += SHFL_XOR(s, 4); s += SHFL_XOR(s, 8); s += SHFL_XOR(s, 16); return s; }
; __device__ __forceinline__ void ssd_sample_step(const bf16* proj, const float* conv_w, const float* conv_b, const float* dt_bias, const float* a_log, const float* d_skip, const float* ssm_norm, ...
;     ...
; #pragma unroll
;     for (int it = 0; it < 16; ++it) { const int k = it >> 2, p = (it & 3) * 16 + pr_; const float xdt = sx[k * 64 + p] * sdt[k];
;         const f32x4 hn = st[it] * sdec[k] + Bv * xdt; LAUNDER_PTR(op); *(f32x4*)op = hn; op += 2048;
;         LAUNDER_PTR(np); if (bg_next >= 0) st[it] = *(const f32x4*)np; np += 2048;
;         const f32x4 t = hn * Cv; float y = (t[0] + t[1]) + (t[2] + t[3]); y = row32_sum(y);
;         if ((lane & 31) == 0) sy[k * 64 + p] = y; }
.LBB0_469:
	s_or_b64 exec, exec, s[14:15]
	ds_read_b32 v78, v81 offset:2176
	s_waitcnt lgkmcnt(0)
	ds_read2_b32 v[76:77], v9 offset1:4
	v_lshl_add_u64 v[84:85], v[84:85], 0, s[44:45]
	v_lshl_add_u64 v[82:83], v[82:83], 0, s[44:45]
	s_and_b64 vcc, exec, s[8:9]
	s_waitcnt lgkmcnt(0)
	v_mul_f32_e32 v76, v78, v76
	v_mov_b32_e32 v78, v77
	v_pk_mul_f32 v[86:87], v[14:15], v[78:79] op_sel_hi:[1,0]
	v_pk_mul_f32 v[88:89], v[12:13], v[78:79] op_sel_hi:[1,0]
	v_pk_fma_f32 v[78:79], v[74:75], v[76:77], v[86:87] op_sel_hi:[1,0,1]
	v_pk_fma_f32 v[76:77], v[72:73], v[76:77], v[88:89] op_sel_hi:[1,0,1]
	global_store_dwordx4 v[82:83], v[76:79], off nt
	s_cbranch_vccnz .LBB0_471
	global_load_dwordx4 v[12:15], v[84:85], off nt

; #define LAUNDER_PTR(p) do {} while (0)
; #define LAUNDER_PTR(p) asm volatile("" : "+v"(p))
; __device__ __forceinline__ float row32_sum(float s) { s += SHFL_XOR(s, 1); s += SHFL_XOR(s, 2); s += SHFL_XOR(s, 4); s += SHFL_XOR(s, 8); s += SHFL_XOR(s, 16); return s; }
; __device__ __forceinline__ void ssd_sample_step(const bf16* proj, const float* conv_w, const float* conv_b, const float* dt_bias, const float* a_log, const float* d_skip, const float* ssm_norm, ...
;     ...
; #pragma unroll
;     for (int it = 0; it < 16; ++it) { const int k = it >> 2, p = (it & 3) * 16 + pr_; const float xdt = sx[k * 64 + p] * sdt[k];
;         const f32x4 hn = st[it] * sdec[k] + Bv * xdt; LAUNDER_PTR(op); *(f32x4*)op = hn; op += 2048;
;         LAUNDER_PTR(np); if (bg_next >= 0) st[it] = *(const f32x4*)np; np += 2048;
;         const f32x4 t = hn * Cv; float y = (t[0] + t[1]) + (t[2] + t[3]); y = row32_sum(y);
;         if ((lane & 31) == 0) sy[k * 64 + p] = y; }
.LBB0_473:
	s_or_b64 exec, exec, s[14:15]
	ds_read_b32 v78, v81 offset:2240
	s_waitcnt lgkmcnt(0)
	ds_read2_b32 v[76:77], v9 offset1:4
	v_lshl_add_u64 v[84:85], v[84:85], 0, s[44:45]
	v_lshl_add_u64 v[82:83], v[82:83], 0, s[44:45]
	s_and_b64 vcc, exec, s[8:9]
	s_waitcnt lgkmcnt(0)
	v_mul_f32_e32 v76, v78, v76
	v_mov_b32_e32 v78, v77
	v_pk_mul_f32 v[86:87], v[18:19], v[78:79] op_sel_hi:[1,0]
	v_pk_mul_f32 v[88:89], v[16:17], v[78:79] op_sel_hi:[1,0]
	v_pk_fma_f32 v[78:79], v[74:75], v[76:77], v[86:87] op_sel_hi:[1,0,1]
	v_pk_fma_f32 v[76:77], v[72:73], v[76:77], v[88:89] op_sel_hi:[1,0,1]
	global_store_dwordx4 v[82:83], v[76:79], off nt
	s_cbranch_vccnz .LBB0_475
	global_load_dwordx4 v[16:19], v[84:85], off nt

; #define LAUNDER_PTR(p) do {} while (0)
; #define LAUNDER_PTR(p) asm volatile("" : "+v"(p))
; __device__ __forceinline__ float row32_sum(float s) { s += SHFL_XOR(s, 1); s += SHFL_XOR(s, 2); s += SHFL_XOR(s, 4); s += SHFL_XOR(s, 8); s += SHFL_XOR(s, 16); return s; }
; __device__ __forceinline__ void ssd_sample_step(const bf16* proj, const float* conv_w, const float* conv_b, const float* dt_bias, const float* a_log, const float* d_skip, const float* ssm_norm, ...
;     ...
; #pragma unroll
;     for (int it = 0; it < 16; ++it) { const int k = it >> 2, p = (it & 3) * 16 + pr_; const float xdt = sx[k * 64 + p] * sdt[k];
;         const f32x4 hn = st[it] * sdec[k] + Bv * xdt; LAUNDER_PTR(op); *(f32x4*)op = hn; op += 2048;
;         LAUNDER_PTR(np); if (bg_next >= 0) st[it] = *(const f32x4*)np; np += 2048;
;         const f32x4 t = hn * Cv; float y = (t[0] + t[1]) + (t[2] + t[3]); y = row32_sum(y);
;         if ((lane & 31) == 0) sy[k * 64 + p] = y; }
.LBB0_477:
	s_or_b64 exec, exec, s[14:15]
	ds_read_b32 v78, v81 offset:2304
	s_waitcnt lgkmcnt(0)
	ds_read2_b32 v[76:77], v9 offset0:1 offset1:5
	v_lshl_add_u64 v[84:85], v[84:85], 0, s[44:45]
	v_lshl_add_u64 v[82:83], v[82:83], 0, s[44:45]
	s_and_b64 vcc, exec, s[8:9]
	s_waitcnt lgkmcnt(0)
	v_mul_f32_e32 v76, v78, v76
	v_mov_b32_e32 v78, v77
	v_pk_mul_f32 v[86:87], v[22:23], v[78:79] op_sel_hi:[1,0]
	v_pk_mul_f32 v[88:89], v[20:21], v[78:79] op_sel_hi:[1,0]
	v_pk_fma_f32 v[78:79], v[74:75], v[76:77], v[86:87] op_sel_hi:[1,0,1]
	v_pk_fma_f32 v[76:77], v[72:73], v[76:77], v[88:89] op_sel_hi:[1,0,1]
	global_store_dwordx4 v[82:83], v[76:79], off nt
	s_cbranch_vccnz .LBB0_479
	global_load_dwordx4 v[20:23], v[84:85], off nt

; #define LAUNDER_PTR(p) do {} while (0)
; #define LAUNDER_PTR(p) asm volatile("" : "+v"(p))
; __device__ __forceinline__ float row32_sum(float s) { s += SHFL_XOR(s, 1); s += SHFL_XOR(s, 2); s += SHFL_XOR(s, 4); s += SHFL_XOR(s, 8); s += SHFL_XOR(s, 16); return s; }
; __device__ __forceinline__ void ssd_sample_step(const bf16* proj, const float* conv_w, const float* conv_b, const float* dt_bias, const float* a_log, const float* d_skip, const float* ssm_norm, ...
;     ...
; #pragma unroll
;     for (int it = 0; it < 16; ++it) { const int k = it >> 2, p = (it & 3) * 16 + pr_; const float xdt = sx[k * 64 + p] * sdt[k];
;         const f32x4 hn = st[it] * sdec[k] + Bv * xdt; LAUNDER_PTR(op); *(f32x4*)op = hn; op += 2048;
;         LAUNDER_PTR(np); if (bg_next >= 0) st[it] = *(const f32x4*)np; np += 2048;
;         const f32x4 t = hn * Cv; float y = (t[0] + t[1]) + (t[2] + t[3]); y = row32_sum(y);
;         if ((lane & 31) == 0) sy[k * 64 + p] = y; }
.LBB0_481:
	s_or_b64 exec, exec, s[14:15]
	ds_read_b32 v78, v81 offset:2368
	s_waitcnt lgkmcnt(0)
	ds_read2_b32 v[76:77], v9 offset0:1 offset1:5
	v_lshl_add_u64 v[84:85], v[84:85], 0, s[44:45]
	v_lshl_add_u64 v[82:83], v[82:83], 0, s[44:45]
	s_and_b64 vcc, exec, s[8:9]
	s_waitcnt lgkmcnt(0)
	v_mul_f32_e32 v76, v78, v76
	v_mov_b32_e32 v78, v77
	v_pk_mul_f32 v[86:87], v[26:27], v[78:79] op_sel_hi:[1,0]
	v_pk_mul_f32 v[88:89], v[24:25], v[78:79] op_sel_hi:[1,0]
	v_pk_fma_f32 v[78:79], v[74:75], v[76:77], v[86:87] op_sel_hi:[1,0,1]
	v_pk_fma_f32 v[76:77], v[72:73], v[76:77], v[88:89] op_sel_hi:[1,0,1]
	global_store_dwordx4 v[82:83], v[76:79], off nt
	s_cbranch_vccnz .LBB0_483
	global_load_dwordx4 v[24:27], v[84:85], off nt

; #define LAUNDER_PTR(p) do {} while (0)
; #define LAUNDER_PTR(p) asm volatile("" : "+v"(p))
; __device__ __forceinline__ float row32_sum(float s) { s += SHFL_XOR(s, 1); s += SHFL_XOR(s, 2); s += SHFL_XOR(s, 4); s += SHFL_XOR(s, 8); s += SHFL_XOR(s, 16); return s; }
; __device__ __forceinline__ void ssd_sample_step(const bf16* proj, const float* conv_w, const float* conv_b, const float* dt_bias, const float* a_log, const float* d_skip, const float* ssm_norm, ...
;     ...
; #pragma unroll
;     for (int it = 0; it < 16; ++it) { const int k = it >> 2, p = (it & 3) * 16 + pr_; const float xdt = sx[k * 64 + p] * sdt[k];
;         const f32x4 hn = st[it] * sdec[k] + Bv * xdt; LAUNDER_PTR(op); *(f32x4*)op = hn; op += 2048;
;         LAUNDER_PTR(np); if (bg_next >= 0) st[it] = *(const f32x4*)np; np += 2048;
;         const f32x4 t = hn * Cv; float y = (t[0] + t[1]) + (t[2] + t[3]); y = row32_sum(y);
;         if ((lane & 31) == 0) sy[k * 64 + p] = y; }
.LBB0_485:
	s_or_b64 exec, exec, s[14:15]
	ds_read_b32 v78, v81 offset:2432
	s_waitcnt lgkmcnt(0)
	ds_read2_b32 v[76:77], v9 offset0:1 offset1:5
	v_lshl_add_u64 v[84:85], v[84:85], 0, s[44:45]
	v_lshl_add_u64 v[82:83], v[82:83], 0, s[44:45]
	s_and_b64 vcc, exec, s[8:9]
	s_waitcnt lgkmcnt(0)
	v_mul_f32_e32 v76, v78, v76
	v_mov_b32_e32 v78, v77
	v_pk_mul_f32 v[86:87], v[30:31], v[78:79] op_sel_hi:[1,0]
	v_pk_mul_f32 v[88:89], v[28:29], v[78:79] op_sel_hi:[1,0]
	v_pk_fma_f32 v[78:79], v[74:75], v[76:77], v[86:87] op_sel_hi:[1,0,1]
	v_pk_fma_f32 v[76:77], v[72:73], v[76:77], v[88:89] op_sel_hi:[1,0,1]
	global_store_dwordx4 v[82:83], v[76:79], off nt
	s_cbranch_vccnz .LBB0_487
	global_load_dwordx4 v[28:31], v[84:85], off nt

; #define LAUNDER_PTR(p) do {} while (0)
; #define LAUNDER_PTR(p) asm volatile("" : "+v"(p))
; __device__ __forceinline__ float row32_sum(float s) { s += SHFL_XOR(s, 1); s += SHFL_XOR(s, 2); s += SHFL_XOR(s, 4); s += SHFL_XOR(s, 8); s += SHFL_XOR(s, 16); return s; }
; __device__ __forceinline__ void ssd_sample_step(const bf16* proj, const float* conv_w, const float* conv_b, const float* dt_bias, const float* a_log, const float* d_skip, const float* ssm_norm, ...
;     ...
; #pragma unroll
;     for (int it = 0; it < 16; ++it) { const int k = it >> 2, p = (it & 3) * 16 + pr_; const float xdt = sx[k * 64 + p] * sdt[k];
;         const f32x4 hn = st[it] * sdec[k] + Bv * xdt; LAUNDER_PTR(op); *(f32x4*)op = hn; op += 2048;
;         LAUNDER_PTR(np); if (bg_next >= 0) st[it] = *(const f32x4*)np; np += 2048;
;         const f32x4 t = hn * Cv; float y = (t[0] + t[1]) + (t[2] + t[3]); y = row32_sum(y);
;         if ((lane & 31) == 0) sy[k * 64 + p] = y; }
.LBB0_489:
	s_or_b64 exec, exec, s[14:15]
	ds_read_b32 v78, v81 offset:2496
	s_waitcnt lgkmcnt(0)
	ds_read2_b32 v[76:77], v9 offset0:1 offset1:5
	v_lshl_add_u64 v[84:85], v[84:85], 0, s[44:45]
	v_lshl_add_u64 v[82:83], v[82:83], 0, s[44:45]
	s_and_b64 vcc, exec, s[8:9]
	s_waitcnt lgkmcnt(0)
	v_mul_f32_e32 v76, v78, v76
	v_mov_b32_e32 v78, v77
	v_pk_mul_f32 v[86:87], v[34:35], v[78:79] op_sel_hi:[1,0]
	v_pk_mul_f32 v[88:89], v[32:33], v[78:79] op_sel_hi:[1,0]
	v_pk_fma_f32 v[78:79], v[74:75], v[76:77], v[86:87] op_sel_hi:[1,0,1]
	v_pk_fma_f32 v[76:77], v[72:73], v[76:77], v[88:89] op_sel_hi:[1,0,1]
	global_store_dwordx4 v[82:83], v[76:79], off nt
	s_cbranch_vccnz .LBB0_491
	global_load_dwordx4 v[32:35], v[84:85], off nt

; #define LAUNDER_PTR(p) do {} while (0)
; #define LAUNDER_PTR(p) asm volatile("" : "+v"(p))
; __device__ __forceinline__ float row32_sum(float s) { s += SHFL_XOR(s, 1); s += SHFL_XOR(s, 2); s += SHFL_XOR(s, 4); s += SHFL_XOR(s, 8); s += SHFL_XOR(s, 16); return s; }
; __device__ __forceinline__ void ssd_sample_step(const bf16* proj, const float* conv_w, const float* conv_b, const float* dt_bias, const float* a_log, const float* d_skip, const float* ssm_norm, ...
;     ...
; #pragma unroll
;     for (int it = 0; it < 16; ++it) { const int k = it >> 2, p = (it & 3) * 16 + pr_; const float xdt = sx[k * 64 + p] * sdt[k];
;         const f32x4 hn = st[it] * sdec[k] + Bv * xdt; LAUNDER_PTR(op); *(f32x4*)op = hn; op += 2048;
;         LAUNDER_PTR(np); if (bg_next >= 0) st[it] = *(const f32x4*)np; np += 2048;
;         const f32x4 t = hn * Cv; float y = (t[0] + t[1]) + (t[2] + t[3]); y = row32_sum(y);
;         if ((lane & 31) == 0) sy[k * 64 + p] = y; }
.LBB0_493:
	s_or_b64 exec, exec, s[14:15]
	ds_read_b32 v78, v81 offset:2560
	s_waitcnt lgkmcnt(0)
	ds_read2_b32 v[76:77], v9 offset0:2 offset1:6
	v_lshl_add_u64 v[84:85], v[84:85], 0, s[44:45]
	v_lshl_add_u64 v[82:83], v[82:83], 0, s[44:45]
	s_and_b64 vcc, exec, s[8:9]
	s_waitcnt lgkmcnt(0)
	v_mul_f32_e32 v76, v78, v76
	v_mov_b32_e32 v78, v77
	v_pk_mul_f32 v[86:87], v[38:39], v[78:79] op_sel_hi:[1,0]
	v_pk_mul_f32 v[88:89], v[36:37], v[78:79] op_sel_hi:[1,0]
	v_pk_fma_f32 v[78:79], v[74:75], v[76:77], v[86:87] op_sel_hi:[1,0,1]
	v_pk_fma_f32 v[76:77], v[72:73], v[76:77], v[88:89] op_sel_hi:[1,0,1]
	global_store_dwordx4 v[82:83], v[76:79], off nt
	s_cbranch_vccnz .LBB0_495
	global_load_dwordx4 v[36:39], v[84:85], off nt

; #define LAUNDER_PTR(p) do {} while (0)
; #define LAUNDER_PTR(p) asm volatile("" : "+v"(p))
; __device__ __forceinline__ float row32_sum(float s) { s += SHFL_XOR(s, 1); s += SHFL_XOR(s, 2); s += SHFL_XOR(s, 4); s += SHFL_XOR(s, 8); s += SHFL_XOR(s, 16); return s; }
; __device__ __forceinline__ void ssd_sample_step(const bf16* proj, const float* conv_w, const float* conv_b, const float* dt_bias, const float* a_log, const float* d_skip, const float* ssm_norm, ...
;     ...
; #pragma unroll
;     for (int it = 0; it < 16; ++it) { const int k = it >> 2, p = (it & 3) * 16 + pr_; const float xdt = sx[k * 64 + p] * sdt[k];
;         const f32x4 hn = st[it] * sdec[k] + Bv * xdt; LAUNDER_PTR(op); *(f32x4*)op = hn; op += 2048;
;         LAUNDER_PTR(np); if (bg_next >= 0) st[it] = *(const f32x4*)np; np += 2048;
;         const f32x4 t = hn * Cv; float y = (t[0] + t[1]) + (t[2] + t[3]); y = row32_sum(y);
;         if ((lane & 31) == 0) sy[k * 64 + p] = y; }
.LBB0_497:
	s_or_b64 exec, exec, s[14:15]
	ds_read_b32 v78, v81 offset:2624
	s_waitcnt lgkmcnt(0)
	ds_read2_b32 v[76:77], v9 offset0:2 offset1:6
	v_lshl_add_u64 v[84:85], v[84:85], 0, s[44:45]
	v_lshl_add_u64 v[82:83], v[82:83], 0, s[44:45]
	s_and_b64 vcc, exec, s[8:9]
	s_waitcnt lgkmcnt(0)
	v_mul_f32_e32 v76, v78, v76
	v_mov_b32_e32 v78, v77
	v_pk_mul_f32 v[86:87], v[42:43], v[78:79] op_sel_hi:[1,0]
	v_pk_mul_f32 v[88:89], v[40:41], v[78:79] op_sel_hi:[1,0]
	v_pk_fma_f32 v[78:79], v[74:75], v[76:77], v[86:87] op_sel_hi:[1,0,1]
	v_pk_fma_f32 v[76:77], v[72:73], v[76:77], v[88:89] op_sel_hi:[1,0,1]
	global_store_dwordx4 v[82:83], v[76:79], off nt
	s_cbranch_vccnz .LBB0_499
	global_load_dwordx4 v[40:43], v[84:85], off nt

; #define LAUNDER_PTR(p) do {} while (0)
; #define LAUNDER_PTR(p) asm volatile("" : "+v"(p))
; __device__ __forceinline__ float row32_sum(float s) { s += SHFL_XOR(s, 1); s += SHFL_XOR(s, 2); s += SHFL_XOR(s, 4); s += SHFL_XOR(s, 8); s += SHFL_XOR(s, 16); return s; }
; __device__ __forceinline__ void ssd_sample_step(const bf16* proj, const float* conv_w, const float* conv_b, const float* dt_bias, const float* a_log, const float* d_skip, const float* ssm_norm, ...
;     ...
; #pragma unroll
;     for (int it = 0; it < 16; ++it) { const int k = it >> 2, p = (it & 3) * 16 + pr_; const float xdt = sx[k * 64 + p] * sdt[k];
;         const f32x4 hn = st[it] * sdec[k] + Bv * xdt; LAUNDER_PTR(op); *(f32x4*)op = hn; op += 2048;
;         LAUNDER_PTR(np); if (bg_next >= 0) st[it] = *(const f32x4*)np; np += 2048;
;         const f32x4 t = hn * Cv; float y = (t[0] + t[1]) + (t[2] + t[3]); y = row32_sum(y);
;         if ((lane & 31) == 0) sy[k * 64 + p] = y; }
.LBB0_501:
	s_or_b64 exec, exec, s[14:15]
	ds_read_b32 v78, v81 offset:2688
	s_waitcnt lgkmcnt(0)
	ds_read2_b32 v[76:77], v9 offset0:2 offset1:6
	v_lshl_add_u64 v[84:85], v[84:85], 0, s[44:45]
	v_lshl_add_u64 v[82:83], v[82:83], 0, s[44:45]
	s_and_b64 vcc, exec, s[8:9]
	s_waitcnt lgkmcnt(0)
	v_mul_f32_e32 v76, v78, v76
	v_mov_b32_e32 v78, v77
	v_pk_mul_f32 v[86:87], v[46:47], v[78:79] op_sel_hi:[1,0]
	v_pk_mul_f32 v[88:89], v[44:45], v[78:79] op_sel_hi:[1,0]
	v_pk_fma_f32 v[78:79], v[74:75], v[76:77], v[86:87] op_sel_hi:[1,0,1]
	v_pk_fma_f32 v[76:77], v[72:73], v[76:77], v[88:89] op_sel_hi:[1,0,1]
	global_store_dwordx4 v[82:83], v[76:79], off nt
	s_cbranch_vccnz .LBB0_503
	global_load_dwordx4 v[44:47], v[84:85], off nt

; #define LAUNDER_PTR(p) do {} while (0)
; #define LAUNDER_PTR(p) asm volatile("" : "+v"(p))
; __device__ __forceinline__ float row32_sum(float s) { s += SHFL_XOR(s, 1); s += SHFL_XOR(s, 2); s += SHFL_XOR(s, 4); s += SHFL_XOR(s, 8); s += SHFL_XOR(s, 16); return s; }
; __device__ __forceinline__ void ssd_sample_step(const bf16* proj, const float* conv_w, const float* conv_b, const float* dt_bias, const float* a_log, const float* d_skip, const float* ssm_norm, ...
;     ...
; #pragma unroll
;     for (int it = 0; it < 16; ++it) { const int k = it >> 2, p = (it & 3) * 16 + pr_; const float xdt = sx[k * 64 + p] * sdt[k];
;         const f32x4 hn = st[it] * sdec[k] + Bv * xdt; LAUNDER_PTR(op); *(f32x4*)op = hn; op += 2048;
;         LAUNDER_PTR(np); if (bg_next >= 0) st[it] = *(const f32x4*)np; np += 2048;
;         const f32x4 t = hn * Cv; float y = (t[0] + t[1]) + (t[2] + t[3]); y = row32_sum(y);
;         if ((lane & 31) == 0) sy[k * 64 + p] = y; }
.LBB0_505:
	s_or_b64 exec, exec, s[14:15]
	ds_read_b32 v78, v81 offset:2752
	s_waitcnt lgkmcnt(0)
	ds_read2_b32 v[76:77], v9 offset0:2 offset1:6
	v_lshl_add_u64 v[84:85], v[84:85], 0, s[44:45]
	v_lshl_add_u64 v[82:83], v[82:83], 0, s[44:45]
	s_and_b64 vcc, exec, s[8:9]
	s_waitcnt lgkmcnt(0)
	v_mul_f32_e32 v76, v78, v76
	v_mov_b32_e32 v78, v77
	v_pk_mul_f32 v[86:87], v[50:51], v[78:79] op_sel_hi:[1,0]
	v_pk_mul_f32 v[88:89], v[48:49], v[78:79] op_sel_hi:[1,0]
	v_pk_fma_f32 v[78:79], v[74:75], v[76:77], v[86:87] op_sel_hi:[1,0,1]
	v_pk_fma_f32 v[76:77], v[72:73], v[76:77], v[88:89] op_sel_hi:[1,0,1]
	global_store_dwordx4 v[82:83], v[76:79], off nt
	s_cbranch_vccnz .LBB0_507
	global_load_dwordx4 v[48:51], v[84:85], off nt

; #define LAUNDER_PTR(p) do {} while (0)
; #define LAUNDER_PTR(p) asm volatile("" : "+v"(p))
; __device__ __forceinline__ float row32_sum(float s) { s += SHFL_XOR(s, 1); s += SHFL_XOR(s, 2); s += SHFL_XOR(s, 4); s += SHFL_XOR(s, 8); s += SHFL_XOR(s, 16); return s; }
; __device__ __forceinline__ void ssd_sample_step(const bf16* proj, const float* conv_w, const float* conv_b, const float* dt_bias, const float* a_log, const float* d_skip, const float* ssm_norm, ...
;     ...
; #pragma unroll
;     for (int it = 0; it < 16; ++it) { const int k = it >> 2, p = (it & 3) * 16 + pr_; const float xdt = sx[k * 64 + p] * sdt[k];
;         const f32x4 hn = st[it] * sdec[k] + Bv * xdt; LAUNDER_PTR(op); *(f32x4*)op = hn; op += 2048;
;         LAUNDER_PTR(np); if (bg_next >= 0) st[it] = *(const f32x4*)np; np += 2048;
;         const f32x4 t = hn * Cv; float y = (t[0] + t[1]) + (t[2] + t[3]); y = row32_sum(y);
;         if ((lane & 31) == 0) sy[k * 64 + p] = y; }
.LBB0_509:
	s_or_b64 exec, exec, s[14:15]
	ds_read_b32 v78, v81 offset:2816
	s_waitcnt lgkmcnt(0)
	ds_read2_b32 v[76:77], v9 offset0:3 offset1:7
	v_lshl_add_u64 v[84:85], v[84:85], 0, s[44:45]
	v_lshl_add_u64 v[82:83], v[82:83], 0, s[44:45]
	s_and_b64 vcc, exec, s[8:9]
	s_waitcnt lgkmcnt(0)
	v_mul_f32_e32 v76, v78, v76
	v_mov_b32_e32 v78, v77
	v_pk_mul_f32 v[86:87], v[54:55], v[78:79] op_sel_hi:[1,0]
	v_pk_mul_f32 v[88:89], v[52:53], v[78:79] op_sel_hi:[1,0]
	v_pk_fma_f32 v[78:79], v[74:75], v[76:77], v[86:87] op_sel_hi:[1,0,1]
	v_pk_fma_f32 v[76:77], v[72:73], v[76:77], v[88:89] op_sel_hi:[1,0,1]
	global_store_dwordx4 v[82:83], v[76:79], off nt
	s_cbranch_vccnz .LBB0_511
	global_load_dwordx4 v[52:55], v[84:85], off nt

; #define LAUNDER_PTR(p) do {} while (0)
; #define LAUNDER_PTR(p) asm volatile("" : "+v"(p))
; __device__ __forceinline__ float row32_sum(float s) { s += SHFL_XOR(s, 1); s += SHFL_XOR(s, 2); s += SHFL_XOR(s, 4); s += SHFL_XOR(s, 8); s += SHFL_XOR(s, 16); return s; }
; __device__ __forceinline__ void ssd_sample_step(const bf16* proj, const float* conv_w, const float* conv_b, const float* dt_bias, const float* a_log, const float* d_skip, const float* ssm_norm, ...
;     ...
; #pragma unroll
;     for (int it = 0; it < 16; ++it) { const int k = it >> 2, p = (it & 3) * 16 + pr_; const float xdt = sx[k * 64 + p] * sdt[k];
;         const f32x4 hn = st[it] * sdec[k] + Bv * xdt; LAUNDER_PTR(op); *(f32x4*)op = hn; op += 2048;
;         LAUNDER_PTR(np); if (bg_next >= 0) st[it] = *(const f32x4*)np; np += 2048;
;         const f32x4 t = hn * Cv; float y = (t[0] + t[1]) + (t[2] + t[3]); y = row32_sum(y);
;         if ((lane & 31) == 0) sy[k * 64 + p] = y; }
.LBB0_513:
	s_or_b64 exec, exec, s[14:15]
	ds_read_b32 v78, v81 offset:2880
	s_waitcnt lgkmcnt(0)
	ds_read2_b32 v[76:77], v9 offset0:3 offset1:7
	v_lshl_add_u64 v[84:85], v[84:85], 0, s[44:45]
	v_lshl_add_u64 v[82:83], v[82:83], 0, s[44:45]
	s_and_b64 vcc, exec, s[8:9]
	s_waitcnt lgkmcnt(0)
	v_mul_f32_e32 v76, v78, v76
	v_mov_b32_e32 v78, v77
	v_pk_mul_f32 v[86:87], v[58:59], v[78:79] op_sel_hi:[1,0]
	v_pk_mul_f32 v[88:89], v[56:57], v[78:79] op_sel_hi:[1,0]
	v_pk_fma_f32 v[78:79], v[74:75], v[76:77], v[86:87] op_sel_hi:[1,0,1]
	v_pk_fma_f32 v[76:77], v[72:73], v[76:77], v[88:89] op_sel_hi:[1,0,1]
	global_store_dwordx4 v[82:83], v[76:79], off nt
	s_cbranch_vccnz .LBB0_515
	global_load_dwordx4 v[56:59], v[84:85], off nt

; #define LAUNDER_PTR(p) do {} while (0)
; #define LAUNDER_PTR(p) asm volatile("" : "+v"(p))
; __device__ __forceinline__ float row32_sum(float s) { s += SHFL_XOR(s, 1); s += SHFL_XOR(s, 2); s += SHFL_XOR(s, 4); s += SHFL_XOR(s, 8); s += SHFL_XOR(s, 16); return s; }
; __device__ __forceinline__ void ssd_sample_step(const bf16* proj, const float* conv_w, const float* conv_b, const float* dt_bias, const float* a_log, const float* d_skip, const float* ssm_norm, ...
;     ...
; #pragma unroll
;     for (int it = 0; it < 16; ++it) { const int k = it >> 2, p = (it & 3) * 16 + pr_; const float xdt = sx[k * 64 + p] * sdt[k];
;         const f32x4 hn = st[it] * sdec[k] + Bv * xdt; LAUNDER_PTR(op); *(f32x4*)op = hn; op += 2048;
;         LAUNDER_PTR(np); if (bg_next >= 0) st[it] = *(const f32x4*)np; np += 2048;
;         const f32x4 t = hn * Cv; float y = (t[0] + t[1]) + (t[2] + t[3]); y = row32_sum(y);
;         if ((lane & 31) == 0) sy[k * 64 + p] = y; }
.LBB0_517:
	s_or_b64 exec, exec, s[14:15]
	ds_read_b32 v78, v81 offset:2944
	s_waitcnt lgkmcnt(0)
	ds_read2_b32 v[76:77], v9 offset0:3 offset1:7
	v_lshl_add_u64 v[84:85], v[84:85], 0, s[44:45]
	v_lshl_add_u64 v[82:83], v[82:83], 0, s[44:45]
	s_and_b64 vcc, exec, s[8:9]
	s_waitcnt lgkmcnt(0)
	v_mul_f32_e32 v76, v78, v76
	v_mov_b32_e32 v78, v77
	v_pk_mul_f32 v[86:87], v[62:63], v[78:79] op_sel_hi:[1,0]
	v_pk_mul_f32 v[88:89], v[60:61], v[78:79] op_sel_hi:[1,0]
	v_pk_fma_f32 v[78:79], v[74:75], v[76:77], v[86:87] op_sel_hi:[1,0,1]
	v_pk_fma_f32 v[76:77], v[72:73], v[76:77], v[88:89] op_sel_hi:[1,0,1]
	global_store_dwordx4 v[82:83], v[76:79], off nt
	s_cbranch_vccnz .LBB0_519
	global_load_dwordx4 v[60:63], v[84:85], off nt

; #define LAUNDER_PTR(p) do {} while (0)
; #define LAUNDER_PTR(p) asm volatile("" : "+v"(p))
; __device__ __forceinline__ float row32_sum(float s) { s += SHFL_XOR(s, 1); s += SHFL_XOR(s, 2); s += SHFL_XOR(s, 4); s += SHFL_XOR(s, 8); s += SHFL_XOR(s, 16); return s; }
; __device__ __forceinline__ void ssd_sample_step(const bf16* proj, const float* conv_w, const float* conv_b, const float* dt_bias, const float* a_log, const float* d_skip, const float* ssm_norm, ...
;     ...
; #pragma unroll
;     for (int it = 0; it < 16; ++it) { const int k = it >> 2, p = (it & 3) * 16 + pr_; const float xdt = sx[k * 64 + p] * sdt[k];
;         const f32x4 hn = st[it] * sdec[k] + Bv * xdt; LAUNDER_PTR(op); *(f32x4*)op = hn; op += 2048;
;         LAUNDER_PTR(np); if (bg_next >= 0) st[it] = *(const f32x4*)np; np += 2048;
;         const f32x4 t = hn * Cv; float y = (t[0] + t[1]) + (t[2] + t[3]); y = row32_sum(y);
;         if ((lane & 31) == 0) sy[k * 64 + p] = y; }
.LBB0_521:
	s_or_b64 exec, exec, s[14:15]
	ds_read_b32 v86, v81 offset:3008
	ds_read2_b32 v[78:79], v9 offset0:3 offset1:7
	s_waitcnt lgkmcnt(0)
	v_lshl_add_u64 v[76:77], v[84:85], 0, s[44:45]
	v_lshl_add_u64 v[82:83], v[82:83], 0, s[44:45]
	s_and_b64 vcc, exec, s[8:9]
	v_mov_b32_e32 v84, v79
	v_mul_f32_e32 v78, v86, v78
	v_pk_mul_f32 v[86:87], v[66:67], v[84:85] op_sel_hi:[1,0]
	v_pk_mul_f32 v[84:85], v[64:65], v[84:85] op_sel_hi:[1,0]
	v_pk_fma_f32 v[74:75], v[74:75], v[78:79], v[86:87] op_sel_hi:[1,0,1]
	v_pk_fma_f32 v[72:73], v[72:73], v[78:79], v[84:85] op_sel_hi:[1,0,1]
	global_store_dwordx4 v[82:83], v[72:75], off nt
	s_cbranch_vccnz .LBB0_523
	global_load_dwordx4 v[64:67], v[76:77], off nt

; #define LAS __attribute__((address_space(3)))
; #define LAUNDER_PTR(p) do {} while (0)
; #define LAUNDER_PTR(p) asm volatile("" : "+v"(p))
; __device__ __forceinline__ void hgrn_sample_step(const bf16* proj, const float* lbs_l, const float* hgn_l, const float* state_in, float* state_out, bf16* ohg, int bh, int tid, LAS unsigned char* lds,
;                                                  f32x4 (&st)[8], int bh_next) {
;     ...
;     const int dv4 = tid & 31, rg = tid >> 5;
;     const f32x4 vv = *(const LAS f32x4*)(sv + 4 * dv4);
;     f32x4 oacc = (f32x4){0.f, 0.f, 0.f, 0.f};
;     float* op = state_out + (size_t)bh * 16384 + tid * 4;
;     const float* np = state_in + (size_t)(bh_next >= 0 ? bh_next : bh) * 16384 + tid * 4;
; #pragma unroll
;     for (int it = 0; it < 8; ++it) { const int dk = it * 16 + rg; const f32x4 sn = st[it] * sg[dk] + vv * sk[dk]; LAUNDER_PTR(op); *(f32x4*)op = sn; op += 2048; oacc = oacc + sn * sq[dk];
;         LAUNDER_PTR(np); if (bh_next >= 0) st[it] = *(const f32x4*)np; np += 2048; }
.LBB0_556:
	s_or_b64 exec, exec, s[8:9]
	v_lshlrev_b32_e32 v40, 2, v8
	v_and_b32_e32 v73, 0x7c, v40
	v_ashrrev_i32_e32 v71, 5, v8
	v_lshl_add_u32 v10, v73, 2, 0
	s_waitcnt lgkmcnt(0)
	s_barrier
	ds_read_b128 v[36:39], v10 offset:1536
	v_lshl_add_u32 v10, v71, 2, 0
	ds_read2st64_b32 v[42:43], v10 offset0:2 offset1:4
	s_add_i32 s17, s18, s90
	s_cmpk_gt_i32 s17, 0x3ff
	s_cselect_b64 s[12:13], -1, 0
	s_cmpk_lt_i32 s17, 0x400
	s_cselect_b32 s8, s17, -1
	v_ashrrev_i32_e32 v41, 31, v40
	v_lshlrev_b64 v[46:47], 2, v[40:41]
	s_cmp_gt_i32 s8, -1
	s_waitcnt lgkmcnt(0)
	v_mov_b32_e32 v40, v43
	s_cselect_b64 s[14:15], -1, 0
	v_pk_mul_f32 v[48:49], v[38:39], v[40:41] op_sel_hi:[1,0]
	v_pk_mul_f32 v[40:41], v[36:37], v[40:41] op_sel_hi:[1,0]
	v_lshl_add_u64 v[44:45], s[2:3], 0, v[46:47]
	s_and_b64 vcc, s[14:15], exec
	v_pk_fma_f32 v[40:41], v[0:1], v[42:43], v[40:41] op_sel_hi:[1,0,1]
	v_pk_fma_f32 v[42:43], v[2:3], v[42:43], v[48:49] op_sel_hi:[1,0,1]
	s_cselect_b32 s8, s8, s18
	global_store_dwordx4 v[44:45], v[40:43], off nt
	s_ashr_i32 s9, s8, 31
	ds_read_b32 v70, v10
	s_lshl_b64 s[8:9], s[8:9], 16
	s_add_u32 s8, s0, s8
	s_addc_u32 s9, s1, s9
	v_lshl_add_u64 v[46:47], s[8:9], 0, v[46:47]
	s_cbranch_vccz .LBB0_558
	global_load_dwordx4 v[0:3], v[46:47], off nt

; #define LAUNDER_PTR(p) do {} while (0)
; #define LAUNDER_PTR(p) asm volatile("" : "+v"(p))
; __device__ __forceinline__ void ssd_sample_load(f32x4 (&st)[16], const float* state_in, int bg, int tid) {
;     const float* sp = state_in + ((size_t)((bg >> 3) * 32 + (bg & 7) * 4)) * 8192 + tid * 4;
; #pragma unroll
;     for (int it = 0; it < 16; ++it) { LAUNDER_PTR(sp); st[it] = *(const f32x4*)sp; sp += 2048; }
; }
.LBB0_578:
	v_readlane_b32 s0, v255, 34
	v_readlane_b32 s1, v255, 35
	v_readlane_b32 s8, v253, 15
	s_lshl_b64 s[0:1], s[0:1], 27
	v_readlane_b32 s14, v253, 21
	v_readlane_b32 s2, v254, 11
	v_readlane_b32 s15, v253, 22
	s_add_u32 s0, s14, s0
	v_readlane_b32 s3, v254, 12
	s_addc_u32 s1, s15, s1
	s_and_b64 vcc, exec, s[2:3]
	v_readlane_b32 s9, v253, 16
	v_readlane_b32 s10, v253, 17
	v_readlane_b32 s11, v253, 18
	v_readlane_b32 s12, v253, 19
	v_readlane_b32 s13, v253, 20
	v_readlane_b32 s16, v253, 23
	v_readlane_b32 s17, v253, 24
	v_readlane_b32 s18, v253, 25
	v_readlane_b32 s19, v253, 26
	v_readlane_b32 s20, v253, 27
	v_readlane_b32 s21, v253, 28
	v_readlane_b32 s22, v253, 29
	v_readlane_b32 s23, v253, 30
	s_cbranch_vccz .LBB0_580
	s_waitcnt vmcnt(0) lgkmcnt(0)
	v_mov_b32_e32 v0, v138
	v_readlane_b32 s2, v254, 15
	v_readlane_b32 s3, v254, 16
	s_add_u32 s2, s0, s2
	v_lshlrev_b32_e32 v0, 2, v0
	s_addc_u32 s3, s1, s3
	v_ashrrev_i32_e32 v1, 31, v0
	v_lshl_add_u64 v[4:5], v[0:1], 2, s[2:3]
	global_load_dwordx4 v[0:3], v[4:5], off nt
	v_lshl_add_u64 v[8:9], v[4:5], 0, s[44:45]
	global_load_dwordx4 v[4:7], v[8:9], off nt
	v_lshl_add_u64 v[8:9], v[8:9], 0, s[44:45]
	global_load_dwordx4 v[12:15], v[8:9], off nt
	v_lshl_add_u64 v[8:9], v[8:9], 0, s[44:45]
	global_load_dwordx4 v[16:19], v[8:9], off nt
	v_lshl_add_u64 v[8:9], v[8:9], 0, s[44:45]
	global_load_dwordx4 v[20:23], v[8:9], off nt
	v_lshl_add_u64 v[8:9], v[8:9], 0, s[44:45]
	global_load_dwordx4 v[24:27], v[8:9], off nt
	v_lshl_add_u64 v[8:9], v[8:9], 0, s[44:45]
	global_load_dwordx4 v[28:31], v[8:9], off nt
	v_lshl_add_u64 v[8:9], v[8:9], 0, s[44:45]
	global_load_dwordx4 v[32:35], v[8:9], off nt
	v_lshl_add_u64 v[8:9], v[8:9], 0, s[44:45]
	global_load_dwordx4 v[36:39], v[8:9], off nt
	v_lshl_add_u64 v[8:9], v[8:9], 0, s[44:45]
	global_load_dwordx4 v[40:43], v[8:9], off nt
	v_lshl_add_u64 v[8:9], v[8:9], 0, s[44:45]
	global_load_dwordx4 v[44:47], v[8:9], off nt
	v_lshl_add_u64 v[8:9], v[8:9], 0, s[44:45]
	global_load_dwordx4 v[48:51], v[8:9], off nt
	v_lshl_add_u64 v[8:9], v[8:9], 0, s[44:45]
	global_load_dwordx4 v[52:55], v[8:9], off nt
	v_lshl_add_u64 v[8:9], v[8:9], 0, s[44:45]
	global_load_dwordx4 v[56:59], v[8:9], off nt
	v_lshl_add_u64 v[8:9], v[8:9], 0, s[44:45]
	global_load_dwordx4 v[60:63], v[8:9], off nt
	v_lshl_add_u64 v[8:9], v[8:9], 0, s[44:45]
	global_load_dwordx4 v[64:67], v[8:9], off nt

; #define LAS __attribute__((address_space(3)))
; #define LAUNDER_PTR(p) do {} while (0)
; #define LAUNDER_PTR(p) asm volatile("" : "+v"(p))
; __device__ __forceinline__ float row32_sum(float s) { s += SHFL_XOR(s, 1); s += SHFL_XOR(s, 2); s += SHFL_XOR(s, 4); s += SHFL_XOR(s, 8); s += SHFL_XOR(s, 16); return s; }
; __device__ __forceinline__ void ssd_sample_step(const bf16* proj, const float* conv_w, const float* conv_b, const float* dt_bias, const float* a_log, const float* d_skip, const float* ssm_norm, ...
;     ...
;     const int n4 = tid & 31, pr_ = tid >> 5;
;     const f32x4 Bv = *(const LAS f32x4*)(sB + 4 * n4), Cv = *(const LAS f32x4*)(sC + 4 * n4);
;     float* op = state_out + ((size_t)(b * 32 + grp * 4)) * 8192 + tid * 4;
;     const int bgn = bg_next >= 0 ? bg_next : bg; const float* np = state_in + ((size_t)((bgn >> 3) * 32 + (bgn & 7) * 4)) * 8192 + tid * 4;
; #pragma unroll
;     for (int it = 0; it < 16; ++it) { const int k = it >> 2, p = (it & 3) * 16 + pr_; const float xdt = sx[k * 64 + p] * sdt[k];
;         const f32x4 hn = st[it] * sdec[k] + Bv * xdt; LAUNDER_PTR(op); *(f32x4*)op = hn; op += 2048;
;         LAUNDER_PTR(np); if (bg_next >= 0) st[it] = *(const f32x4*)np; np += 2048;
;         const f32x4 t = hn * Cv; float y = (t[0] + t[1]) + (t[2] + t[3]); y = row32_sum(y);
;         if ((lane & 31) == 0) sy[k * 64 + p] = y; }
.LBB0_605:
	s_or_b64 exec, exec, s[6:7]
	s_add_i32 s29, s51, s90
	s_cmpk_gt_i32 s29, 0x3ff
	s_cselect_b64 s[12:13], -1, 0
	s_cmpk_lt_i32 s29, 0x400
	s_cselect_b32 s8, s29, -1
	s_lshl_b32 s6, s50, 5
	s_lshl_b32 s50, s28, 2
	s_or_b32 s6, s6, s50
	s_ashr_i32 s7, s6, 31
	s_lshl_b64 s[6:7], s[6:7], 15
	s_add_u32 s6, s20, s6
	v_lshlrev_b32_e32 v72, 2, v8
	s_addc_u32 s7, s21, s7
	v_ashrrev_i32_e32 v73, 31, v72
	s_cmp_gt_i32 s8, -1
	v_lshlrev_b32_e32 v68, 4, v8
	v_lshlrev_b64 v[76:77], 2, v[72:73]
	s_cselect_b64 s[14:15], -1, 0
	v_ashrrev_i32_e32 v9, 5, v8
	v_and_b32_e32 v68, 0x1f0, v68
	v_lshl_add_u64 v[82:83], s[6:7], 0, v[76:77]
	s_and_b64 s[6:7], s[14:15], exec
	s_movk_i32 s9, 0x1000
	v_add_u32_e32 v74, 0, v68
	s_cselect_b32 s6, s8, s51
	v_lshl_add_u32 v81, v9, 2, 0
	v_add_u32_e64 v9, s9, 0
	s_waitcnt lgkmcnt(0)
	s_barrier
	ds_read_b128 v[68:71], v74 offset:3584
	s_lshl_b32 s6, s6, 2
	ds_read_b128 v[72:75], v74 offset:3072
	ds_read_b32 v86, v81 offset:2048
	ds_read2_b32 v[78:79], v9 offset1:4
	s_ashr_i32 s7, s6, 31
	s_lshl_b64 s[6:7], s[6:7], 15
	s_add_u32 s6, s0, s6
	s_addc_u32 s7, s1, s7
	v_lshl_add_u64 v[84:85], s[6:7], 0, v[76:77]
	s_waitcnt lgkmcnt(0)
	v_mov_b32_e32 v76, v79
	v_mul_f32_e32 v78, v86, v78
	v_pk_mul_f32 v[86:87], v[2:3], v[76:77] op_sel_hi:[1,0]
	v_pk_mul_f32 v[76:77], v[0:1], v[76:77] op_sel_hi:[1,0]
	s_cmp_lt_i32 s8, 0
	v_pk_fma_f32 v[76:77], v[72:73], v[78:79], v[76:77] op_sel_hi:[1,0,1]
	v_pk_fma_f32 v[78:79], v[74:75], v[78:79], v[86:87] op_sel_hi:[1,0,1]
	global_store_dwordx4 v[82:83], v[76:79], off nt
	s_cbranch_scc1 .LBB0_607
	global_load_dwordx4 v[0:3], v[84:85], off nt
